# grid barrier: release directly on the TOP arrival counter (all workgroups poll TOP >= (gen+1)*nx); TOPGEN hop removed
# baseline (speedup 1.0000x reference)
.LBB0_60:
	s_or_b64 exec, exec, s[8:9]
	v_cvt_f32_u32_e32 v4, v2
	s_waitcnt vmcnt(0)
	v_readfirstlane_b32 s3, v3
	v_sub_u32_e32 v3, 0, v2
	v_rcp_iflag_f32_e32 v4, v4
	v_add_u32_e32 v5, s3, v1
	v_mul_f32_e32 v4, 0x4f7ffffe, v4
	v_cvt_u32_f32_e32 v4, v4
	v_mul_lo_u32 v1, v3, v4
	v_mul_hi_u32 v1, v4, v1
	v_add_u32_e32 v1, v4, v1
	v_mul_hi_u32 v1, v5, v1
	v_mul_lo_u32 v3, v1, v2
	v_sub_u32_e32 v3, v5, v3
	v_add_u32_e32 v4, 1, v1
	v_cmp_ge_u32_e32 vcc, v3, v2
	s_nop 1
	v_cndmask_b32_e32 v1, v1, v4, vcc
	v_sub_u32_e32 v4, v3, v2
	v_cndmask_b32_e32 v3, v3, v4, vcc
	v_add_u32_e32 v4, 1, v1
	v_cmp_ge_u32_e32 vcc, v3, v2
	v_add_u32_e32 v3, 1, v5
	s_nop 0
	v_cndmask_b32_e32 v1, v1, v4, vcc
	v_mul_lo_u32 v4, v2, v1
	v_add_u32_e32 v2, v4, v2
	v_cmp_ne_u32_e32 vcc, v3, v2
	s_and_saveexec_b64 s[6:7], vcc
	s_xor_b64 s[6:7], exec, s[6:7]
	s_cbranch_execz .LBB0_74
	s_waitcnt lgkmcnt(0)
	v_add_u32_e32 v1, 1, v1
	v_mul_lo_u32 v1, v1, v0
	s_add_u32 s12, s24, 0xed25400
	s_addc_u32 s13, s25, 0
	v_mov_b32_e32 v0, 0
	global_load_dword v0, v0, s[12:13] sc1
	s_waitcnt vmcnt(0)
	v_cmp_lt_u32_e32 vcc, v0, v1
	s_and_saveexec_b64 s[8:9], vcc
	s_cbranch_execz .LBB0_73
	s_add_u32 s10, s24, 0xed22200
	s_addc_u32 s11, s25, 0
	s_mov_b32 s3, 1
	s_mov_b64 s[14:15], 0
	v_mov_b32_e32 v0, 0
	s_branch .LBB0_64

.LBB0_66:
	global_load_dword v2, v0, s[12:13] sc1
	s_add_i32 s3, s3, 1
	s_mov_b64 s[28:29], -1
	s_waitcnt vmcnt(0)
	v_cmp_ge_u32_e32 vcc, v2, v1
	s_orn2_b64 s[16:17], vcc, exec
	s_branch .LBB0_63

.LBB0_77:
	s_or_b64 exec, exec, s[8:9]
	v_cvt_f32_u32_e32 v3, v0
	s_waitcnt vmcnt(0)
	v_readfirstlane_b32 s3, v2
	s_add_u32 s8, s24, 0xed25400
	s_addc_u32 s9, s25, 0
	v_rcp_iflag_f32_e32 v3, v3
	v_add_u32_e32 v1, s3, v1
	v_add_u32_e32 v4, 1, v1
	s_mov_b64 s[10:11], 0
	v_mul_f32_e32 v2, 0x4f7ffffe, v3
	v_cvt_u32_f32_e32 v2, v2
	v_sub_u32_e32 v3, 0, v0
	v_mul_lo_u32 v3, v3, v2
	v_mul_hi_u32 v3, v2, v3
	v_add_u32_e32 v2, v2, v3
	v_mul_hi_u32 v2, v1, v2
	v_mul_lo_u32 v3, v2, v0
	v_sub_u32_e32 v1, v1, v3
	v_add_u32_e32 v5, 1, v2
	v_cmp_ge_u32_e32 vcc, v1, v0
	v_sub_u32_e32 v3, v1, v0
	s_nop 0
	v_cndmask_b32_e32 v2, v2, v5, vcc
	v_cndmask_b32_e32 v1, v1, v3, vcc
	v_add_u32_e32 v3, 1, v2
	v_cmp_ge_u32_e32 vcc, v1, v0
	s_nop 1
	v_cndmask_b32_e32 v2, v2, v3, vcc
	v_mul_lo_u32 v1, v0, v2
	v_add_u32_e32 v0, v1, v0
	v_cmp_ne_u32_e32 vcc, v4, v0
	v_readfirstlane_b32 s100, v0
	v_mov_b64_e32 v[0:1], s[8:9]
	s_and_saveexec_b64 s[6:7], vcc
	s_cbranch_execz .LBB0_89
	v_mov_b32_e32 v0, 0
	global_load_dword v1, v0, s[8:9] sc1
	s_mov_b64 s[14:15], 0
	s_waitcnt vmcnt(0)
	v_cmp_gt_u32_e32 vcc, s100, v1
	s_and_saveexec_b64 s[12:13], vcc
	s_cbranch_execz .LBB0_88
	s_add_u32 s10, s24, 0xed22200
	s_addc_u32 s11, s25, 0
	s_mov_b32 s3, 1
	s_branch .LBB0_81

.LBB0_83:
	global_load_dword v1, v0, s[8:9] sc1
	s_add_i32 s3, s3, 1
	s_mov_b64 s[16:17], -1
	s_waitcnt vmcnt(0)
	v_cmp_le_u32_e32 vcc, s100, v1
	s_orn2_b64 s[34:35], vcc, exec
	s_branch .LBB0_80

.LBB0_205:
	s_or_b64 exec, exec, s[10:11]
	v_cvt_f32_u32_e32 v3, v0
	s_waitcnt vmcnt(0)
	v_readfirstlane_b32 s3, v2
	s_add_u32 s10, s24, 0xed25400
	s_addc_u32 s11, s25, 0
	v_rcp_iflag_f32_e32 v3, v3
	v_add_u32_e32 v1, s3, v1
	v_add_u32_e32 v4, 1, v1
	s_mov_b64 s[12:13], 0
	v_mul_f32_e32 v2, 0x4f7ffffe, v3
	v_cvt_u32_f32_e32 v2, v2
	v_sub_u32_e32 v3, 0, v0
	v_mul_lo_u32 v3, v3, v2
	v_mul_hi_u32 v3, v2, v3
	v_add_u32_e32 v2, v2, v3
	v_mul_hi_u32 v2, v1, v2
	v_mul_lo_u32 v3, v2, v0
	v_sub_u32_e32 v1, v1, v3
	v_add_u32_e32 v5, 1, v2
	v_cmp_ge_u32_e32 vcc, v1, v0
	v_sub_u32_e32 v3, v1, v0
	s_nop 0
	v_cndmask_b32_e32 v2, v2, v5, vcc
	v_cndmask_b32_e32 v1, v1, v3, vcc
	v_add_u32_e32 v3, 1, v2
	v_cmp_ge_u32_e32 vcc, v1, v0
	s_nop 1
	v_cndmask_b32_e32 v2, v2, v3, vcc
	v_mul_lo_u32 v1, v0, v2
	v_add_u32_e32 v0, v1, v0
	v_cmp_ne_u32_e32 vcc, v4, v0
	v_readfirstlane_b32 s100, v0
	v_mov_b64_e32 v[0:1], s[10:11]
	s_and_saveexec_b64 s[8:9], vcc
	s_cbranch_execz .LBB0_217
	v_mov_b32_e32 v0, 0
	global_load_dword v1, v0, s[10:11] sc1
	s_mov_b64 s[16:17], 0
	s_waitcnt vmcnt(0)
	v_cmp_gt_u32_e32 vcc, s100, v1
	s_and_saveexec_b64 s[14:15], vcc
	s_cbranch_execz .LBB0_216
	s_add_u32 s12, s24, 0xed22200
	s_addc_u32 s13, s25, 0
	s_mov_b32 s3, 1
	s_mov_b64 s[34:35], 0
	s_branch .LBB0_209

.LBB0_211:
	global_load_dword v1, v0, s[10:11] sc1
	s_add_i32 s3, s3, 1
	s_mov_b64 s[16:17], -1
	s_waitcnt vmcnt(0)
	v_cmp_le_u32_e32 vcc, s100, v1
	s_orn2_b64 s[80:81], vcc, exec
	s_branch .LBB0_208

.LBB0_796:
	s_or_b64 exec, exec, s[10:11]
	v_cvt_f32_u32_e32 v3, v0
	s_waitcnt vmcnt(0)
	v_readfirstlane_b32 s3, v2
	s_add_u32 s10, s24, 0xed25400
	s_addc_u32 s11, s25, 0
	v_rcp_iflag_f32_e32 v3, v3
	v_add_u32_e32 v1, s3, v1
	v_add_u32_e32 v4, 1, v1
	s_mov_b64 s[12:13], 0
	v_mul_f32_e32 v2, 0x4f7ffffe, v3
	v_cvt_u32_f32_e32 v2, v2
	v_sub_u32_e32 v3, 0, v0
	v_mul_lo_u32 v3, v3, v2
	v_mul_hi_u32 v3, v2, v3
	v_add_u32_e32 v2, v2, v3
	v_mul_hi_u32 v2, v1, v2
	v_mul_lo_u32 v3, v2, v0
	v_sub_u32_e32 v1, v1, v3
	v_add_u32_e32 v5, 1, v2
	v_cmp_ge_u32_e32 vcc, v1, v0
	v_sub_u32_e32 v3, v1, v0
	s_nop 0
	v_cndmask_b32_e32 v2, v2, v5, vcc
	v_cndmask_b32_e32 v1, v1, v3, vcc
	v_add_u32_e32 v3, 1, v2
	v_cmp_ge_u32_e32 vcc, v1, v0
	s_nop 1
	v_cndmask_b32_e32 v2, v2, v3, vcc
	v_mul_lo_u32 v1, v0, v2
	v_add_u32_e32 v0, v1, v0
	v_cmp_ne_u32_e32 vcc, v4, v0
	v_readfirstlane_b32 s100, v0
	v_mov_b64_e32 v[0:1], s[10:11]
	s_and_saveexec_b64 s[8:9], vcc
	s_cbranch_execz .LBB0_808
	v_mov_b32_e32 v0, 0
	global_load_dword v1, v0, s[10:11] sc1
	s_mov_b64 s[16:17], 0
	s_waitcnt vmcnt(0)
	v_cmp_gt_u32_e32 vcc, s100, v1
	s_and_saveexec_b64 s[14:15], vcc
	s_cbranch_execz .LBB0_807
	s_add_u32 s12, s24, 0xed22200
	s_addc_u32 s13, s25, 0
	s_mov_b32 s3, 1
	s_mov_b64 s[56:57], 0
	s_branch .LBB0_800

.LBB0_802:
	global_load_dword v1, v0, s[10:11] sc1
	s_add_i32 s3, s3, 1
	s_mov_b64 s[16:17], -1
	s_waitcnt vmcnt(0)
	v_cmp_le_u32_e32 vcc, s100, v1
	s_orn2_b64 s[62:63], vcc, exec
	s_branch .LBB0_799

.LBB0_954:
	s_or_b64 exec, exec, s[12:13]
	v_cvt_f32_u32_e32 v4, v2
	s_waitcnt vmcnt(0)
	v_readfirstlane_b32 s3, v3
	v_sub_u32_e32 v3, 0, v2
	v_rcp_iflag_f32_e32 v4, v4
	v_add_u32_e32 v5, s3, v1
	v_mul_f32_e32 v4, 0x4f7ffffe, v4
	v_cvt_u32_f32_e32 v4, v4
	v_mul_lo_u32 v1, v3, v4
	v_mul_hi_u32 v1, v4, v1
	v_add_u32_e32 v1, v4, v1
	v_mul_hi_u32 v1, v5, v1
	v_mul_lo_u32 v3, v1, v2
	v_sub_u32_e32 v3, v5, v3
	v_add_u32_e32 v4, 1, v1
	v_cmp_ge_u32_e32 vcc, v3, v2
	s_nop 1
	v_cndmask_b32_e32 v1, v1, v4, vcc
	v_sub_u32_e32 v4, v3, v2
	v_cndmask_b32_e32 v3, v3, v4, vcc
	v_add_u32_e32 v4, 1, v1
	v_cmp_ge_u32_e32 vcc, v3, v2
	v_add_u32_e32 v3, 1, v5
	s_nop 0
	v_cndmask_b32_e32 v1, v1, v4, vcc
	v_mul_lo_u32 v4, v2, v1
	v_add_u32_e32 v2, v4, v2
	v_cmp_ne_u32_e32 vcc, v3, v2
	s_and_saveexec_b64 s[10:11], vcc
	s_xor_b64 s[10:11], exec, s[10:11]
	s_cbranch_execz .LBB0_968
	s_waitcnt lgkmcnt(0)
	v_add_u32_e32 v1, 1, v1
	v_mul_lo_u32 v1, v1, v0
	s_add_u32 s42, s24, 0xed25400
	s_addc_u32 s43, s25, 0
	v_mov_b32_e32 v0, 0
	global_load_dword v0, v0, s[42:43] sc1
	s_waitcnt vmcnt(0)
	v_cmp_lt_u32_e32 vcc, v0, v1
	s_and_saveexec_b64 s[12:13], vcc
	s_cbranch_execz .LBB0_967
	s_add_u32 s40, s24, 0xed22200
	s_addc_u32 s41, s25, 0
	s_mov_b32 s3, 1
	s_mov_b64 s[46:47], 0
	v_mov_b32_e32 v0, 0
	s_branch .LBB0_958

.LBB0_960:
	global_load_dword v2, v0, s[42:43] sc1
	s_add_i32 s3, s3, 1
	s_mov_b64 s[28:29], -1
	s_waitcnt vmcnt(0)
	v_cmp_ge_u32_e32 vcc, v2, v1
	s_orn2_b64 s[16:17], vcc, exec
	s_branch .LBB0_957

.LBB0_971:
	s_or_b64 exec, exec, s[16:17]
	v_cvt_f32_u32_e32 v3, v0
	s_waitcnt vmcnt(0)
	v_readfirstlane_b32 s3, v2
	s_add_u32 s40, s24, 0xed25400
	s_addc_u32 s41, s25, 0
	v_rcp_iflag_f32_e32 v3, v3
	v_add_u32_e32 v1, s3, v1
	v_add_u32_e32 v4, 1, v1
	s_mov_b64 s[16:17], 0
	v_mul_f32_e32 v2, 0x4f7ffffe, v3
	v_cvt_u32_f32_e32 v2, v2
	v_sub_u32_e32 v3, 0, v0
	v_mul_lo_u32 v3, v3, v2
	v_mul_hi_u32 v3, v2, v3
	v_add_u32_e32 v2, v2, v3
	v_mul_hi_u32 v2, v1, v2
	v_mul_lo_u32 v3, v2, v0
	v_sub_u32_e32 v1, v1, v3
	v_add_u32_e32 v5, 1, v2
	v_cmp_ge_u32_e32 vcc, v1, v0
	v_sub_u32_e32 v3, v1, v0
	s_nop 0
	v_cndmask_b32_e32 v2, v2, v5, vcc
	v_cndmask_b32_e32 v1, v1, v3, vcc
	v_add_u32_e32 v3, 1, v2
	v_cmp_ge_u32_e32 vcc, v1, v0
	s_nop 1
	v_cndmask_b32_e32 v2, v2, v3, vcc
	v_mul_lo_u32 v1, v0, v2
	v_add_u32_e32 v0, v1, v0
	v_cmp_ne_u32_e32 vcc, v4, v0
	v_readfirstlane_b32 s100, v0
	v_mov_b64_e32 v[0:1], s[40:41]
	s_and_saveexec_b64 s[12:13], vcc
	s_cbranch_execz .LBB0_983
	v_mov_b32_e32 v0, 0
	global_load_dword v1, v0, s[40:41] sc1
	s_mov_b64 s[16:17], 0
	s_waitcnt vmcnt(0)
	v_cmp_gt_u32_e32 vcc, s100, v1
	s_and_saveexec_b64 s[46:47], vcc
	s_cbranch_execz .LBB0_982
	s_add_u32 s42, s24, 0xed22200
	s_addc_u32 s43, s25, 0
	s_mov_b32 s3, 1
	s_mov_b64 s[48:49], 0
	s_branch .LBB0_975

.LBB0_977:
	global_load_dword v1, v0, s[40:41] sc1
	s_add_i32 s3, s3, 1
	s_mov_b64 s[16:17], -1
	s_waitcnt vmcnt(0)
	v_cmp_le_u32_e32 vcc, s100, v1
	s_orn2_b64 s[56:57], vcc, exec
	s_branch .LBB0_974

.LBB0_1090:
	s_or_b64 exec, exec, s[16:17]
	v_cvt_f32_u32_e32 v4, v2
	s_waitcnt vmcnt(0)
	v_readfirstlane_b32 s3, v3
	v_sub_u32_e32 v3, 0, v2
	v_rcp_iflag_f32_e32 v4, v4
	v_add_u32_e32 v5, s3, v1
	v_mul_f32_e32 v4, 0x4f7ffffe, v4
	v_cvt_u32_f32_e32 v4, v4
	v_mul_lo_u32 v1, v3, v4
	v_mul_hi_u32 v1, v4, v1
	v_add_u32_e32 v1, v4, v1
	v_mul_hi_u32 v1, v5, v1
	v_mul_lo_u32 v3, v1, v2
	v_sub_u32_e32 v3, v5, v3
	v_add_u32_e32 v4, 1, v1
	v_cmp_ge_u32_e32 vcc, v3, v2
	s_nop 1
	v_cndmask_b32_e32 v1, v1, v4, vcc
	v_sub_u32_e32 v4, v3, v2
	v_cndmask_b32_e32 v3, v3, v4, vcc
	v_add_u32_e32 v4, 1, v1
	v_cmp_ge_u32_e32 vcc, v3, v2
	v_add_u32_e32 v3, 1, v5
	s_nop 0
	v_cndmask_b32_e32 v1, v1, v4, vcc
	v_mul_lo_u32 v4, v2, v1
	v_add_u32_e32 v2, v4, v2
	v_cmp_ne_u32_e32 vcc, v3, v2
	s_and_saveexec_b64 s[6:7], vcc
	s_xor_b64 s[6:7], exec, s[6:7]
	s_cbranch_execz .LBB0_1104
	s_waitcnt lgkmcnt(0)
	v_add_u32_e32 v1, 1, v1
	v_mul_lo_u32 v1, v1, v0
	s_add_u32 s46, s24, 0xed25400
	s_addc_u32 s47, s25, 0
	v_mov_b32_e32 v0, 0
	global_load_dword v0, v0, s[46:47] sc1
	s_waitcnt vmcnt(0)
	v_cmp_lt_u32_e32 vcc, v0, v1
	s_and_saveexec_b64 s[40:41], vcc
	s_cbranch_execz .LBB0_1103
	s_add_u32 s42, s24, 0xed22200
	s_addc_u32 s43, s25, 0
	s_mov_b32 s3, 1
	s_mov_b64 s[48:49], 0
	v_mov_b32_e32 v0, 0
	s_branch .LBB0_1094

.LBB0_1096:
	global_load_dword v2, v0, s[46:47] sc1
	s_add_i32 s3, s3, 1
	s_mov_b64 s[28:29], -1
	s_waitcnt vmcnt(0)
	v_cmp_ge_u32_e32 vcc, v2, v1
	s_orn2_b64 s[16:17], vcc, exec
	s_branch .LBB0_1093

.LBB0_1107:
	s_or_b64 exec, exec, s[28:29]
	v_cvt_f32_u32_e32 v3, v0
	s_waitcnt vmcnt(0)
	v_readfirstlane_b32 s3, v2
	s_add_u32 s42, s24, 0xed25400
	s_addc_u32 s43, s25, 0
	v_rcp_iflag_f32_e32 v3, v3
	v_add_u32_e32 v1, s3, v1
	v_add_u32_e32 v4, 1, v1
	s_mov_b64 s[16:17], 0
	v_mul_f32_e32 v2, 0x4f7ffffe, v3
	v_cvt_u32_f32_e32 v2, v2
	v_sub_u32_e32 v3, 0, v0
	v_mul_lo_u32 v3, v3, v2
	v_mul_hi_u32 v3, v2, v3
	v_add_u32_e32 v2, v2, v3
	v_mul_hi_u32 v2, v1, v2
	v_mul_lo_u32 v3, v2, v0
	v_sub_u32_e32 v1, v1, v3
	v_add_u32_e32 v5, 1, v2
	v_cmp_ge_u32_e32 vcc, v1, v0
	v_sub_u32_e32 v3, v1, v0
	s_nop 0
	v_cndmask_b32_e32 v2, v2, v5, vcc
	v_cndmask_b32_e32 v1, v1, v3, vcc
	v_add_u32_e32 v3, 1, v2
	v_cmp_ge_u32_e32 vcc, v1, v0
	s_nop 1
	v_cndmask_b32_e32 v2, v2, v3, vcc
	v_mul_lo_u32 v1, v0, v2
	v_add_u32_e32 v0, v1, v0
	v_cmp_ne_u32_e32 vcc, v4, v0
	v_readfirstlane_b32 s100, v0
	v_mov_b64_e32 v[0:1], s[42:43]
	s_and_saveexec_b64 s[40:41], vcc
	s_cbranch_execz .LBB0_1119
	v_mov_b32_e32 v0, 0
	global_load_dword v1, v0, s[42:43] sc1
	s_mov_b64 s[16:17], 0
	s_waitcnt vmcnt(0)
	v_cmp_gt_u32_e32 vcc, s100, v1
	s_and_saveexec_b64 s[48:49], vcc
	s_cbranch_execz .LBB0_1118
	s_add_u32 s46, s24, 0xed22200
	s_addc_u32 s47, s25, 0
	s_mov_b32 s3, 1
	s_mov_b64 s[52:53], 0
	s_branch .LBB0_1111

.LBB0_1113:
	global_load_dword v1, v0, s[42:43] sc1
	s_add_i32 s3, s3, 1
	s_mov_b64 s[16:17], -1
	s_waitcnt vmcnt(0)
	v_cmp_le_u32_e32 vcc, s100, v1
	s_orn2_b64 s[62:63], vcc, exec
	s_branch .LBB0_1110

.LBB0_1220:
	s_or_b64 exec, exec, s[16:17]
	v_cvt_f32_u32_e32 v4, v2
	s_waitcnt vmcnt(0)
	v_readfirstlane_b32 s3, v3
	v_sub_u32_e32 v3, 0, v2
	v_rcp_iflag_f32_e32 v4, v4
	v_add_u32_e32 v5, s3, v1
	v_mul_f32_e32 v4, 0x4f7ffffe, v4
	v_cvt_u32_f32_e32 v4, v4
	v_mul_lo_u32 v1, v3, v4
	v_mul_hi_u32 v1, v4, v1
	v_add_u32_e32 v1, v4, v1
	v_mul_hi_u32 v1, v5, v1
	v_mul_lo_u32 v3, v1, v2
	v_sub_u32_e32 v3, v5, v3
	v_add_u32_e32 v4, 1, v1
	v_cmp_ge_u32_e32 vcc, v3, v2
	s_nop 1
	v_cndmask_b32_e32 v1, v1, v4, vcc
	v_sub_u32_e32 v4, v3, v2
	v_cndmask_b32_e32 v3, v3, v4, vcc
	v_add_u32_e32 v4, 1, v1
	v_cmp_ge_u32_e32 vcc, v3, v2
	v_add_u32_e32 v3, 1, v5
	s_nop 0
	v_cndmask_b32_e32 v1, v1, v4, vcc
	v_mul_lo_u32 v4, v2, v1
	v_add_u32_e32 v2, v4, v2
	v_cmp_ne_u32_e32 vcc, v3, v2
	s_and_saveexec_b64 s[6:7], vcc
	s_xor_b64 s[6:7], exec, s[6:7]
	s_cbranch_execz .LBB0_1234
	s_waitcnt lgkmcnt(0)
	v_add_u32_e32 v1, 1, v1
	v_mul_lo_u32 v1, v1, v0
	s_add_u32 s40, s24, 0xed25400
	s_addc_u32 s41, s25, 0
	v_mov_b32_e32 v0, 0
	global_load_dword v0, v0, s[40:41] sc1
	s_waitcnt vmcnt(0)
	v_cmp_lt_u32_e32 vcc, v0, v1
	s_and_saveexec_b64 s[36:37], vcc
	s_cbranch_execz .LBB0_1233
	s_add_u32 s38, s24, 0xed22200
	s_addc_u32 s39, s25, 0
	s_mov_b32 s3, 1
	s_mov_b64 s[42:43], 0
	v_mov_b32_e32 v0, 0
	s_branch .LBB0_1224

.LBB0_1226:
	global_load_dword v2, v0, s[40:41] sc1
	s_add_i32 s3, s3, 1
	s_mov_b64 s[28:29], -1
	s_waitcnt vmcnt(0)
	v_cmp_ge_u32_e32 vcc, v2, v1
	s_orn2_b64 s[16:17], vcc, exec
	s_branch .LBB0_1223

.LBB0_1237:
	s_or_b64 exec, exec, s[16:17]
	v_cvt_f32_u32_e32 v3, v0
	s_waitcnt vmcnt(0)
	v_readfirstlane_b32 s3, v2
	s_add_u32 s36, s24, 0xed25400
	s_addc_u32 s37, s25, 0
	v_rcp_iflag_f32_e32 v3, v3
	v_add_u32_e32 v1, s3, v1
	v_add_u32_e32 v4, 1, v1
	s_mov_b64 s[16:17], 0
	v_mul_f32_e32 v2, 0x4f7ffffe, v3
	v_cvt_u32_f32_e32 v2, v2
	v_sub_u32_e32 v3, 0, v0
	v_mul_lo_u32 v3, v3, v2
	v_mul_hi_u32 v3, v2, v3
	v_add_u32_e32 v2, v2, v3
	v_mul_hi_u32 v2, v1, v2
	v_mul_lo_u32 v3, v2, v0
	v_sub_u32_e32 v1, v1, v3
	v_add_u32_e32 v5, 1, v2
	v_cmp_ge_u32_e32 vcc, v1, v0
	v_sub_u32_e32 v3, v1, v0
	s_nop 0
	v_cndmask_b32_e32 v2, v2, v5, vcc
	v_cndmask_b32_e32 v1, v1, v3, vcc
	v_add_u32_e32 v3, 1, v2
	v_cmp_ge_u32_e32 vcc, v1, v0
	s_nop 1
	v_cndmask_b32_e32 v2, v2, v3, vcc
	v_mul_lo_u32 v1, v0, v2
	v_add_u32_e32 v0, v1, v0
	v_cmp_ne_u32_e32 vcc, v4, v0
	v_readfirstlane_b32 s100, v0
	v_mov_b64_e32 v[0:1], s[36:37]
	s_and_saveexec_b64 s[6:7], vcc
	s_cbranch_execz .LBB0_1249
	v_mov_b32_e32 v0, 0
	global_load_dword v1, v0, s[36:37] sc1
	s_mov_b64 s[16:17], 0
	s_waitcnt vmcnt(0)
	v_cmp_gt_u32_e32 vcc, s100, v1
	s_and_saveexec_b64 s[40:41], vcc
	s_cbranch_execz .LBB0_1248
	s_add_u32 s38, s24, 0xed22200
	s_addc_u32 s39, s25, 0
	s_mov_b32 s3, 1
	s_mov_b64 s[42:43], 0
	s_branch .LBB0_1241

.LBB0_1243:
	global_load_dword v1, v0, s[36:37] sc1
	s_add_i32 s3, s3, 1
	s_mov_b64 s[16:17], -1
	s_waitcnt vmcnt(0)
	v_cmp_le_u32_e32 vcc, s100, v1
	s_orn2_b64 s[48:49], vcc, exec
	s_branch .LBB0_1240

.LBB0_1318:
	s_or_b64 exec, exec, s[14:15]
	v_cvt_f32_u32_e32 v4, v2
	s_waitcnt vmcnt(0)
	v_readfirstlane_b32 s3, v3
	v_sub_u32_e32 v3, 0, v2
	v_rcp_iflag_f32_e32 v4, v4
	v_add_u32_e32 v5, s3, v1
	v_mul_f32_e32 v4, 0x4f7ffffe, v4
	v_cvt_u32_f32_e32 v4, v4
	v_mul_lo_u32 v1, v3, v4
	v_mul_hi_u32 v1, v4, v1
	v_add_u32_e32 v1, v4, v1
	v_mul_hi_u32 v1, v5, v1
	v_mul_lo_u32 v3, v1, v2
	v_sub_u32_e32 v3, v5, v3
	v_add_u32_e32 v4, 1, v1
	v_cmp_ge_u32_e32 vcc, v3, v2
	s_nop 1
	v_cndmask_b32_e32 v1, v1, v4, vcc
	v_sub_u32_e32 v4, v3, v2
	v_cndmask_b32_e32 v3, v3, v4, vcc
	v_add_u32_e32 v4, 1, v1
	v_cmp_ge_u32_e32 vcc, v3, v2
	v_add_u32_e32 v3, 1, v5
	s_nop 0
	v_cndmask_b32_e32 v1, v1, v4, vcc
	v_mul_lo_u32 v4, v2, v1
	v_add_u32_e32 v2, v4, v2
	v_cmp_ne_u32_e32 vcc, v3, v2
	s_and_saveexec_b64 s[6:7], vcc
	s_xor_b64 s[6:7], exec, s[6:7]
	s_cbranch_execz .LBB0_1332
	s_waitcnt lgkmcnt(0)
	v_add_u32_e32 v1, 1, v1
	v_mul_lo_u32 v1, v1, v0
	s_add_u32 s38, s24, 0xed25400
	s_addc_u32 s39, s25, 0
	v_mov_b32_e32 v0, 0
	global_load_dword v0, v0, s[38:39] sc1
	s_waitcnt vmcnt(0)
	v_cmp_lt_u32_e32 vcc, v0, v1
	s_and_saveexec_b64 s[14:15], vcc
	s_cbranch_execz .LBB0_1331
	s_add_u32 s36, s24, 0xed22200
	s_addc_u32 s37, s25, 0
	s_mov_b32 s3, 1
	s_mov_b64 s[40:41], 0
	v_mov_b32_e32 v0, 0
	s_branch .LBB0_1322

.LBB0_1324:
	global_load_dword v2, v0, s[38:39] sc1
	s_add_i32 s3, s3, 1
	s_mov_b64 s[28:29], -1
	s_waitcnt vmcnt(0)
	v_cmp_ge_u32_e32 vcc, v2, v1
	s_orn2_b64 s[16:17], vcc, exec
	s_branch .LBB0_1321

.LBB0_1335:
	s_or_b64 exec, exec, s[16:17]
	v_cvt_f32_u32_e32 v3, v0
	s_waitcnt vmcnt(0)
	v_readfirstlane_b32 s3, v2
	s_add_u32 s36, s24, 0xed25400
	s_addc_u32 s37, s25, 0
	v_rcp_iflag_f32_e32 v3, v3
	v_add_u32_e32 v1, s3, v1
	v_add_u32_e32 v4, 1, v1
	s_mov_b64 s[16:17], 0
	v_mul_f32_e32 v2, 0x4f7ffffe, v3
	v_cvt_u32_f32_e32 v2, v2
	v_sub_u32_e32 v3, 0, v0
	v_mul_lo_u32 v3, v3, v2
	v_mul_hi_u32 v3, v2, v3
	v_add_u32_e32 v2, v2, v3
	v_mul_hi_u32 v2, v1, v2
	v_mul_lo_u32 v3, v2, v0
	v_sub_u32_e32 v1, v1, v3
	v_add_u32_e32 v5, 1, v2
	v_cmp_ge_u32_e32 vcc, v1, v0
	v_sub_u32_e32 v3, v1, v0
	s_nop 0
	v_cndmask_b32_e32 v2, v2, v5, vcc
	v_cndmask_b32_e32 v1, v1, v3, vcc
	v_add_u32_e32 v3, 1, v2
	v_cmp_ge_u32_e32 vcc, v1, v0
	s_nop 1
	v_cndmask_b32_e32 v2, v2, v3, vcc
	v_mul_lo_u32 v1, v0, v2
	v_add_u32_e32 v0, v1, v0
	v_cmp_ne_u32_e32 vcc, v4, v0
	v_readfirstlane_b32 s100, v0
	v_mov_b64_e32 v[0:1], s[36:37]
	s_and_saveexec_b64 s[14:15], vcc
	s_cbranch_execz .LBB0_1347
	v_mov_b32_e32 v0, 0
	global_load_dword v1, v0, s[36:37] sc1
	s_mov_b64 s[16:17], 0
	s_waitcnt vmcnt(0)
	v_cmp_gt_u32_e32 vcc, s100, v1
	s_and_saveexec_b64 s[40:41], vcc
	s_cbranch_execz .LBB0_1346
	s_add_u32 s38, s24, 0xed22200
	s_addc_u32 s39, s25, 0
	s_mov_b32 s3, 1
	s_mov_b64 s[42:43], 0
	s_branch .LBB0_1339

.LBB0_1414:
	global_load_dword v1, v0, s[36:37] sc1
	s_add_i32 s3, s3, 1
	s_mov_b64 s[16:17], -1
	s_waitcnt vmcnt(0)
	v_cmp_le_u32_e32 vcc, s100, v1
	s_orn2_b64 s[46:47], vcc, exec
	s_branch .LBB0_1411

.LBB0_1522:
	s_or_b64 exec, exec, s[8:9]
	v_cvt_f32_u32_e32 v4, v2
	s_waitcnt vmcnt(0)
	v_readfirstlane_b32 s6, v3
	v_sub_u32_e32 v3, 0, v2
	v_rcp_iflag_f32_e32 v4, v4
	v_add_u32_e32 v5, s6, v1
	v_mul_f32_e32 v4, 0x4f7ffffe, v4
	v_cvt_u32_f32_e32 v4, v4
	v_mul_lo_u32 v1, v3, v4
	v_mul_hi_u32 v1, v4, v1
	v_add_u32_e32 v1, v4, v1
	v_mul_hi_u32 v1, v5, v1
	v_mul_lo_u32 v3, v1, v2
	v_sub_u32_e32 v3, v5, v3
	v_add_u32_e32 v4, 1, v1
	v_cmp_ge_u32_e32 vcc, v3, v2
	s_nop 1
	v_cndmask_b32_e32 v1, v1, v4, vcc
	v_sub_u32_e32 v4, v3, v2
	v_cndmask_b32_e32 v3, v3, v4, vcc
	v_add_u32_e32 v4, 1, v1
	v_cmp_ge_u32_e32 vcc, v3, v2
	v_add_u32_e32 v3, 1, v5
	s_nop 0
	v_cndmask_b32_e32 v1, v1, v4, vcc
	v_mul_lo_u32 v4, v2, v1
	v_add_u32_e32 v2, v4, v2
	v_cmp_ne_u32_e32 vcc, v3, v2
	s_and_saveexec_b64 s[6:7], vcc
	s_xor_b64 s[6:7], exec, s[6:7]
	s_cbranch_execz .LBB0_1536
	s_waitcnt lgkmcnt(0)
	v_add_u32_e32 v1, 1, v1
	v_mul_lo_u32 v1, v1, v0
	s_add_u32 s14, s24, 0xed25400
	s_addc_u32 s15, s25, 0
	v_mov_b32_e32 v0, 0
	global_load_dword v0, v0, s[14:15] sc1
	s_waitcnt vmcnt(0)
	v_cmp_lt_u32_e32 vcc, v0, v1
	s_and_saveexec_b64 s[8:9], vcc
	s_cbranch_execz .LBB0_1535
	s_add_u32 s12, s24, 0xed22200
	s_addc_u32 s13, s25, 0
	s_mov_b32 s19, 1
	s_mov_b64 s[16:17], 0
	v_mov_b32_e32 v0, 0
	s_branch .LBB0_1526

.LBB0_1528:
	global_load_dword v2, v0, s[14:15] sc1
	s_add_i32 s19, s19, 1
	s_mov_b64 s[36:37], -1
	s_waitcnt vmcnt(0)
	v_cmp_ge_u32_e32 vcc, v2, v1
	s_orn2_b64 s[30:31], vcc, exec
	s_branch .LBB0_1525

.LBB0_1539:
	s_or_b64 exec, exec, s[8:9]
	v_cvt_f32_u32_e32 v3, v0
	s_waitcnt vmcnt(0)
	v_readfirstlane_b32 s6, v2
	s_add_u32 s8, s24, 0xed25400
	s_addc_u32 s9, s25, 0
	v_rcp_iflag_f32_e32 v3, v3
	v_add_u32_e32 v1, s6, v1
	v_add_u32_e32 v4, 1, v1
	s_mov_b64 s[12:13], 0
	v_mul_f32_e32 v2, 0x4f7ffffe, v3
	v_cvt_u32_f32_e32 v2, v2
	v_sub_u32_e32 v3, 0, v0
	v_mul_lo_u32 v3, v3, v2
	v_mul_hi_u32 v3, v2, v3
	v_add_u32_e32 v2, v2, v3
	v_mul_hi_u32 v2, v1, v2
	v_mul_lo_u32 v3, v2, v0
	v_sub_u32_e32 v1, v1, v3
	v_add_u32_e32 v5, 1, v2
	v_cmp_ge_u32_e32 vcc, v1, v0
	v_sub_u32_e32 v3, v1, v0
	s_nop 0
	v_cndmask_b32_e32 v2, v2, v5, vcc
	v_cndmask_b32_e32 v1, v1, v3, vcc
	v_add_u32_e32 v3, 1, v2
	v_cmp_ge_u32_e32 vcc, v1, v0
	s_nop 1
	v_cndmask_b32_e32 v2, v2, v3, vcc
	v_mul_lo_u32 v1, v0, v2
	v_add_u32_e32 v0, v1, v0
	v_cmp_ne_u32_e32 vcc, v4, v0
	v_readfirstlane_b32 s100, v0
	v_mov_b64_e32 v[0:1], s[8:9]
	s_and_saveexec_b64 s[6:7], vcc
	s_cbranch_execz .LBB0_1551
	v_mov_b32_e32 v0, 0
	global_load_dword v1, v0, s[8:9] sc1
	s_mov_b64 s[16:17], 0
	s_waitcnt vmcnt(0)
	v_cmp_gt_u32_e32 vcc, s100, v1
	s_and_saveexec_b64 s[14:15], vcc
	s_cbranch_execz .LBB0_1550
	s_add_u32 s12, s24, 0xed22200
	s_addc_u32 s13, s25, 0
	s_mov_b32 s19, 1
	s_branch .LBB0_1543

.LBB0_1545:
	global_load_dword v1, v0, s[8:9] sc1
	s_add_i32 s19, s19, 1
	s_mov_b64 s[30:31], -1
	s_waitcnt vmcnt(0)
	v_cmp_le_u32_e32 vcc, s100, v1
	s_orn2_b64 s[38:39], vcc, exec
	s_branch .LBB0_1542
